# combined: attn loop reschedule (R1) + SGPR-base LDS-DMA in GEMM loops + P8 requant load hoist
# speedup vs baseline: 1.0083x; 1.0083x over previous
; #define SBAR() __builtin_amdgcn_sched_barrier(0)
; #define SLOAD(i, k0) do { const char* vb_ = (const char*)Vh + (size_t)(k0) * (LDV * 2); const char* kb_ = (const char*)Kh + (size_t)(k0) * (LDKK * 2); \
;     sr_[i].vs0 = *(const bf16x8*)(vb_ + voff); sr_[i].vs1 = *(const bf16x8*)(vb_ + 32 * LDV * 2 + voff); \
;     sr_[i].ks0 = *(const bf16x8*)(kb_ + koff); sr_[i].ks1 = *(const bf16x8*)(kb_ + 32 * LDKK * 2 + koff); } while (0)
; __device__ __forceinline__ void finishSM(f32x16& p0, f32x16& p1, float alpha, float& l_reg, bf16x8& pa0, bf16x8& pa1, bf16x8& pa2, bf16x8& pa3) {
;   for (int r = 0; r < 16; ++r) p1[r] = __builtin_amdgcn_exp2f(p1[r]);
;   float ps = 0; for (int r = 0; r < 16; ++r) ps += p0[r]; for (int r = 0; r < 16; ++r) ps += p1[r];
;   { auto rr = __builtin_amdgcn_permlane32_swap(__float_as_uint(ps), __float_as_uint(ps), false, false);
;     ps = __uint_as_float(rr[0]) + __uint_as_float(rr[1]); }
;   l_reg = l_reg * alpha + ps;
;   ATT_PK4(p0, 0, pa0); ATT_PK4(p0, 8, pa1); ATT_PK4(p1, 0, pa2); ATT_PK4(p1, 8, pa3);
; }
; __device__ __forceinline__ void qkt(f32x16& p0, f32x16& p1, const bf16_t* Ks, const bf16x8* qr, int r32, int hi) {
;   p0 = f32x16{}; p1 = f32x16{};
;   for (int d0 = 0; d0 < 8; ++d0) { int cb = (d0 * 16 + hi * 8) * 2;
;     bf16x8 b0 = *reinterpret_cast<const bf16x8*>((const char*)Ks + KSWZ(r32, cb));
;     bf16x8 b1 = *reinterpret_cast<const bf16x8*>((const char*)Ks + KSWZ(32 + r32, cb));
;     p0 = __builtin_amdgcn_mfma_f32_32x32x16_bf16(b0, qr[d0], p0, 0, 0, 0);
;     p1 = __builtin_amdgcn_mfma_f32_32x32x16_bf16(b1, qr[d0], p1, 0, 0, 0); }
; template <bool FAST> __device__ __forceinline__ void attn_dense_body(const bf16_t* __restrict__ Qb, const bf16_t* __restrict__ Kh, const bf16_t* __restrict__ Vh, ...
;     ...
;     SBAR(); qkt(pB0, pB1, (bf16_t*)((char*)K_lds + SHM_K), qr, r32, hi);
;     fsm<FAST>(pA0, pA1, alA, l_reg, pa0, pa1, pa2, pa3); SBAR();
;     SLOAD(SO, (j + 2) * KVBLK); SBAR();
;     pv_d0(o, vb0, pa0, pa1, pa2, pa3); psm<FAST>(pB0, pB1, m_reg, mnB, alB);
.Lattn_h1:
	s_waitcnt lgkmcnt(3)
	v_mfma_f32_32x32x16_bf16 v[98:113], v[172:175], v[144:147], 0
	v_exp_f32_e32 v239, v66
	v_exp_f32_e32 v240, v67
	v_add_f32_e32 v202, 0, v229
	s_waitcnt lgkmcnt(2)
	v_mfma_f32_32x32x16_bf16 v[82:97], v[176:179], v[144:147], 0
	ds_read_b128 v[172:175], v219 offset:49152
	ds_read_b128 v[176:179], v219 offset:57344
	v_exp_f32_e32 v241, v68
	v_exp_f32_e32 v242, v69
	v_add_f32_e32 v202, v230, v202
	s_waitcnt lgkmcnt(3)
	v_mfma_f32_32x32x16_bf16 v[98:113], v[164:167], v[140:143], v[98:113]
	v_exp_f32_e32 v243, v70
	v_exp_f32_e32 v244, v71
	v_add_f32_e32 v202, v231, v202
	s_waitcnt lgkmcnt(2)
	v_mfma_f32_32x32x16_bf16 v[82:97], v[168:171], v[140:143], v[82:97]
	ds_read_b128 v[164:167], v216 offset:49152
	ds_read_b128 v[168:171], v216 offset:57344
	v_exp_f32_e32 v245, v72
	v_exp_f32_e32 v246, v73
	v_add_f32_e32 v202, v233, v202
	s_waitcnt lgkmcnt(3)
	v_mfma_f32_32x32x16_bf16 v[98:113], v[172:175], v[136:139], v[98:113]
	v_cvt_pk_bf16_f32 v66, v229, v230
	v_cvt_pk_bf16_f32 v67, v231, v233
	v_cvt_pk_bf16_f32 v68, v234, v236
	v_cvt_pk_bf16_f32 v69, v232, v235
	v_add_f32_e32 v202, v234, v202
	s_waitcnt lgkmcnt(2)
	v_mfma_f32_32x32x16_bf16 v[82:97], v[176:179], v[136:139], v[82:97]
	ds_read_b128 v[172:175], v215 offset:49152
	ds_read_b128 v[176:179], v215 offset:57344
	v_add_f32_e32 v202, v236, v202
	v_add_f32_e32 v202, v232, v202
	v_permlane32_swap_b32_e32 v66, v68
	v_permlane32_swap_b32_e32 v67, v69
	v_exp_f32_e32 v247, v74
	s_waitcnt lgkmcnt(3)
	v_mfma_f32_32x32x16_bf16 v[98:113], v[164:167], v[132:135], v[98:113]
	v_exp_f32_e32 v248, v75
	v_add_f32_e32 v202, v235, v202
	v_add_f32_e32 v202, v199, v202
	v_add_f32_e32 v202, v200, v202
	s_waitcnt lgkmcnt(2)
	v_mfma_f32_32x32x16_bf16 v[82:97], v[168:171], v[132:135], v[82:97]
	ds_read_b128 v[164:167], v214 offset:49152
	ds_read_b128 v[168:171], v214 offset:57344
	v_cvt_pk_bf16_f32 v70, v199, v200
	v_cvt_pk_bf16_f32 v71, v201, v227
	v_cvt_pk_bf16_f32 v72, v198, v225
	v_cvt_pk_bf16_f32 v73, v226, v228
	v_add_f32_e32 v202, v201, v202
	s_waitcnt lgkmcnt(3)
	v_mfma_f32_32x32x16_bf16 v[98:113], v[172:175], v[128:131], v[98:113]
	v_add_f32_e32 v202, v227, v202
	v_add_f32_e32 v202, v198, v202
	v_permlane32_swap_b32_e32 v70, v72
	v_permlane32_swap_b32_e32 v71, v73
	s_waitcnt vmcnt(0)
	ds_write_b128 v220, v[156:159] offset:32768
	ds_write_b128 v222, v[160:163] offset:32768
	s_waitcnt lgkmcnt(4)
	v_mfma_f32_32x32x16_bf16 v[82:97], v[176:179], v[128:131], v[82:97]
	ds_read_b128 v[172:175], v213 offset:49152
	ds_read_b128 v[176:179], v213 offset:57344
	v_exp_f32_e32 v249, v76
	v_exp_f32_e32 v250, v77
	v_add_f32_e32 v202, v225, v202
	s_waitcnt lgkmcnt(5)
	v_mfma_f32_32x32x16_bf16 v[98:113], v[164:167], v[124:127], v[98:113]
	v_exp_f32_e32 v251, v78
	v_exp_f32_e32 v252, v79
	v_add_f32_e32 v202, v226, v202
	s_waitcnt lgkmcnt(4)
	v_mfma_f32_32x32x16_bf16 v[82:97], v[168:171], v[124:127], v[82:97]
	ds_read_b128 v[164:167], v224 offset:49152
	ds_read_b128 v[168:171], v224 offset:57344
	v_exp_f32_e32 v182, v80
	v_exp_f32_e32 v183, v81
	v_add_f32_e32 v202, v228, v202
	s_waitcnt lgkmcnt(3)
	v_mfma_f32_32x32x16_bf16 v[98:113], v[172:175], v[120:123], v[98:113]
	v_cvt_pk_bf16_f32 v74, v239, v240
	v_cvt_pk_bf16_f32 v75, v241, v242
	v_cvt_pk_bf16_f32 v76, v243, v244
	v_cvt_pk_bf16_f32 v77, v245, v246
	s_waitcnt lgkmcnt(2)
	v_mfma_f32_32x32x16_bf16 v[82:97], v[176:179], v[120:123], v[82:97]
	v_cvt_pk_bf16_f32 v78, v247, v248
	v_cvt_pk_bf16_f32 v79, v249, v250
	v_permlane32_swap_b32_e32 v74, v76
	v_permlane32_swap_b32_e32 v75, v77
	ds_read_b64_tr_b16 v[198:199], v180 offset:0
	ds_read_b64_tr_b16 v[200:201], v180 offset:2048
	s_waitcnt lgkmcnt(3)
	v_mfma_f32_32x32x16_bf16 v[98:113], v[164:167], v[116:119], v[98:113]
	v_cvt_pk_bf16_f32 v80, v251, v252
	v_cvt_pk_bf16_f32 v81, v182, v183
	ds_read_b64_tr_b16 v[226:227], v180 offset:4096
	ds_read_b64_tr_b16 v[228:229], v180 offset:6144
	ds_read_b64_tr_b16 v[230:231], v180 offset:8192
	ds_read_b64_tr_b16 v[232:233], v180 offset:10240
	s_waitcnt lgkmcnt(6)
	v_mfma_f32_32x32x16_bf16 v[82:97], v[168:171], v[116:119], v[82:97]
	ds_read_b64_tr_b16 v[234:235], v180 offset:12288
	ds_read_b64_tr_b16 v[236:237], v180 offset:14336
	v_permlane32_swap_b32_e32 v78, v80
	v_permlane32_swap_b32_e32 v79, v81
	s_waitcnt lgkmcnt(6)
	v_mfma_f32_32x32x16_bf16 v[2:17], v[66:69], v[198:201], v[2:17]
	ds_read_b64_tr_b16 v[198:199], v180 offset:512
	ds_read_b64_tr_b16 v[200:201], v180 offset:2560
	v_add_f32_e32 v202, v239, v202
	v_exp_f32_e32 v239, v98
	v_lshl_add_u64 v[188:189], v[196:197], 0, s[48:49]
	v_lshl_add_u64 v[186:187], v[194:195], 0, s[48:49]
	s_waitcnt lgkmcnt(6)
	v_mfma_f32_32x32x16_bf16 v[2:17], v[70:73], v[226:229], v[2:17]
	ds_read_b64_tr_b16 v[226:227], v180 offset:4608
	ds_read_b64_tr_b16 v[228:229], v180 offset:6656
	v_add_f32_e32 v202, v240, v202
	v_exp_f32_e32 v240, v99
	v_add_co_u32_e32 v164, vcc, s62, v188
	s_mov_b32 s3, 0x5f238000
	s_waitcnt lgkmcnt(6)
	v_mfma_f32_32x32x16_bf16 v[2:17], v[74:77], v[230:233], v[2:17]
	ds_read_b64_tr_b16 v[230:231], v180 offset:8704
	ds_read_b64_tr_b16 v[232:233], v180 offset:10752
	v_add_f32_e32 v202, v241, v202
	v_exp_f32_e32 v241, v100
	v_addc_co_u32_e32 v165, vcc, 0, v189, vcc
	v_add_co_u32_e32 v168, vcc, s59, v188
	s_waitcnt lgkmcnt(6)
	v_mfma_f32_32x32x16_bf16 v[2:17], v[78:81], v[234:237], v[2:17]
	ds_read_b64_tr_b16 v[234:235], v180 offset:12800
	ds_read_b64_tr_b16 v[236:237], v180 offset:14848
	v_add_f32_e32 v202, v242, v202
	v_exp_f32_e32 v242, v101
	global_load_dwordx4 v[164:167], v[164:165], off offset:1024
	v_addc_co_u32_e32 v169, vcc, 0, v189, vcc
	v_add_co_u32_e32 v172, vcc, s24, v186
	s_waitcnt lgkmcnt(6)
; #define SBAR() __builtin_amdgcn_sched_barrier(0)
; #define SLOAD(i, k0) do { const char* vb_ = (const char*)Vh + (size_t)(k0) * (LDV * 2); const char* kb_ = (const char*)Kh + (size_t)(k0) * (LDKK * 2); \
;     sr_[i].vs0 = *(const bf16x8*)(vb_ + voff); sr_[i].vs1 = *(const bf16x8*)(vb_ + 32 * LDV * 2 + voff); \
;     sr_[i].ks0 = *(const bf16x8*)(kb_ + koff); sr_[i].ks1 = *(const bf16x8*)(kb_ + 32 * LDKK * 2 + koff); } while (0)
; #define SWAIT() asm volatile("s_waitcnt vmcnt(4)" ::: "memory")
; template <int D0> __device__ __forceinline__ void pv_one(f32x16& od, int vb, bf16x8 pa0, bf16x8 pa1, bf16x8 pa2, bf16x8 pa3) {
;   const s16x4 l0 = tr_read<v_rd_off(D0, 0, 0)>(vb), h0 = tr_read<v_rd_off(D0, 0, 1)>(vb), l1 = tr_read<v_rd_off(D0, 1, 0)>(vb), h1 = tr_read<v_rd_off(D0, 1, 1)>(vb);
;   const s16x4 l2 = tr_read<v_rd_off(D0, 2, 0)>(vb), h2 = tr_read<v_rd_off(D0, 2, 1)>(vb), l3 = tr_read<v_rd_off(D0, 3, 0)>(vb), h3 = tr_read<v_rd_off(D0, 3, 1)>(vb);
;   asm volatile("s_waitcnt lgkmcnt(0)" ::: "memory"); SBAR();
;   od = __builtin_amdgcn_mfma_f32_32x32x16_bf16(pa0, ATT_PK(l0, h0), od, 0, 0, 0);
;   od = __builtin_amdgcn_mfma_f32_32x32x16_bf16(pa1, ATT_PK(l1, h1), od, 0, 0, 0);
;   od = __builtin_amdgcn_mfma_f32_32x32x16_bf16(pa2, ATT_PK(l2, h2), od, 0, 0, 0);
;   od = __builtin_amdgcn_mfma_f32_32x32x16_bf16(pa3, ATT_PK(l3, h3), od, 0, 0, 0);
; }
; __device__ __forceinline__ void pv_d0(f32x16* o, int vb, bf16x8 pa0, bf16x8 pa1, bf16x8 pa2, bf16x8 pa3) {
;   pv_one<0>(o[0], vb, pa0, pa1, pa2, pa3); pv_one<1>(o[1], vb, pa0, pa1, pa2, pa3); pv_one<2>(o[2], vb, pa0, pa1, pa2, pa3); pv_one<3>(o[3], vb, pa0, pa1, pa2, pa3);
; template <bool FAST> __device__ __forceinline__ void attn_dense_body(const bf16_t* __restrict__ Qb, const bf16_t* __restrict__ Kh, const bf16_t* __restrict__ Vh, ...
;     ...
;     pv_d0(o, vb0, pa0, pa1, pa2, pa3); psm<FAST>(pB0, pB1, m_reg, mnB, alB);
;     __syncthreads(); SWAIT(); SWRITE(0, SE);
;     if constexpr (!FAST) RESC(alB); __syncthreads();
;     SBAR(); qkt(pA0, pA1, K_lds, qr, r32, hi);
;     fsm<FAST>(pB0, pB1, alB, l_reg, pa0, pa1, pa2, pa3); SBAR();
;     if (j + 3 < NT) SLOAD(SE, (j + 3) * KVBLK); SBAR();
;     pv_d0(o, vb0 + (int)SHM_V, pa0, pa1, pa2, pa3); psm<FAST>(pA0, pA1, m_reg, mnA, alA);
	v_mfma_f32_32x32x16_bf16 v[18:33], v[66:69], v[198:201], v[18:33]
	ds_read_b64_tr_b16 v[198:199], v180 offset:1024
	ds_read_b64_tr_b16 v[200:201], v180 offset:3072
	v_add_f32_e32 v202, v243, v202
	v_exp_f32_e32 v243, v102
	global_load_dwordx4 v[168:171], v[168:169], off offset:1024
	v_addc_co_u32_e32 v173, vcc, 0, v187, vcc
	v_add_co_u32_e32 v176, vcc, s3, v186
	s_waitcnt lgkmcnt(6)
	v_mfma_f32_32x32x16_bf16 v[18:33], v[70:73], v[226:229], v[18:33]
	ds_read_b64_tr_b16 v[226:227], v180 offset:5120
	ds_read_b64_tr_b16 v[228:229], v180 offset:7168
	v_add_f32_e32 v202, v244, v202
	v_exp_f32_e32 v244, v103
	global_load_dwordx4 v[172:175], v[172:173], off
	v_addc_co_u32_e32 v177, vcc, 0, v187, vcc
	s_waitcnt lgkmcnt(6)
	v_mfma_f32_32x32x16_bf16 v[18:33], v[74:77], v[230:233], v[18:33]
	ds_read_b64_tr_b16 v[230:231], v180 offset:9216
	ds_read_b64_tr_b16 v[232:233], v180 offset:11264
	v_add_f32_e32 v202, v245, v202
	v_exp_f32_e32 v245, v104
	v_add_f32_e32 v202, v246, v202
	v_exp_f32_e32 v246, v105
	global_load_dwordx4 v[176:179], v[176:177], off
	s_waitcnt lgkmcnt(6)
	v_mfma_f32_32x32x16_bf16 v[18:33], v[78:81], v[234:237], v[18:33]
	ds_read_b64_tr_b16 v[234:235], v180 offset:13312
	ds_read_b64_tr_b16 v[236:237], v180 offset:15360
	v_add_f32_e32 v202, v247, v202
	v_exp_f32_e32 v247, v106
	v_add_f32_e32 v202, v248, v202
	v_exp_f32_e32 v248, v107
	s_waitcnt lgkmcnt(6)
	v_mfma_f32_32x32x16_bf16 v[34:49], v[66:69], v[198:201], v[34:49]
	ds_read_b64_tr_b16 v[198:199], v180 offset:1536
	ds_read_b64_tr_b16 v[200:201], v180 offset:3584
	v_add_f32_e32 v202, v249, v202
	v_exp_f32_e32 v249, v108
	v_add_f32_e32 v202, v250, v202
	v_exp_f32_e32 v250, v109
	s_waitcnt lgkmcnt(6)
	v_mfma_f32_32x32x16_bf16 v[34:49], v[70:73], v[226:229], v[34:49]
	ds_read_b64_tr_b16 v[226:227], v180 offset:5632
	ds_read_b64_tr_b16 v[228:229], v180 offset:7680
	v_add_f32_e32 v202, v251, v202
	v_exp_f32_e32 v251, v110
	v_add_f32_e32 v202, v252, v202
	v_exp_f32_e32 v252, v111
	s_waitcnt lgkmcnt(6)
	v_mfma_f32_32x32x16_bf16 v[34:49], v[74:77], v[230:233], v[34:49]
	ds_read_b64_tr_b16 v[230:231], v180 offset:9728
	ds_read_b64_tr_b16 v[232:233], v180 offset:11776
	v_add_f32_e32 v202, v182, v202
	v_exp_f32_e32 v182, v112
	v_add_f32_e32 v202, v183, v202
	v_exp_f32_e32 v183, v113
	s_waitcnt lgkmcnt(6)
	v_mfma_f32_32x32x16_bf16 v[34:49], v[78:81], v[234:237], v[34:49]
	ds_read_b64_tr_b16 v[234:235], v180 offset:13824
	ds_read_b64_tr_b16 v[236:237], v180 offset:15872
	v_mov_b32_e32 v238, v202
	s_waitcnt lgkmcnt(0)
	v_mfma_f32_32x32x16_bf16 v[50:65], v[66:69], v[198:201], v[50:65]
	s_barrier
	ds_write_b128 v217, v[148:151] offset:0
	ds_write_b128 v218, v[152:155] offset:0
	ds_read_b128 v[156:159], v221 offset:32768
	ds_read_b128 v[160:163], v221 offset:40960
	v_permlane32_swap_b32_e32 v202, v238
	v_mfma_f32_32x32x16_bf16 v[50:65], v[70:73], v[226:229], v[50:65]
	v_add_f32_e32 v238, v202, v238
	v_add_f32_e32 v1, v1, v238
	ds_read_b128 v[148:151], v223 offset:32768
	ds_read_b128 v[152:155], v223 offset:40960
	v_mfma_f32_32x32x16_bf16 v[50:65], v[74:77], v[230:233], v[50:65]
	v_mfma_f32_32x32x16_bf16 v[50:65], v[78:81], v[234:237], v[50:65]
	s_waitcnt lgkmcnt(3)
	v_mfma_f32_32x32x16_bf16 v[98:113], v[156:159], v[144:147], 0
	v_exp_f32_e32 v229, v82
	v_exp_f32_e32 v230, v83
	v_add_f32_e32 v202, 0, v239
	s_waitcnt lgkmcnt(2)
	v_mfma_f32_32x32x16_bf16 v[66:81], v[160:163], v[144:147], 0
	ds_read_b128 v[156:159], v219 offset:32768
	ds_read_b128 v[160:163], v219 offset:40960
	v_exp_f32_e32 v231, v84
	v_exp_f32_e32 v233, v85
	v_add_f32_e32 v202, v240, v202
	s_waitcnt lgkmcnt(3)
	v_mfma_f32_32x32x16_bf16 v[98:113], v[148:151], v[140:143], v[98:113]
	v_exp_f32_e32 v234, v86
	v_exp_f32_e32 v236, v87
	v_add_f32_e32 v202, v241, v202
	s_waitcnt lgkmcnt(2)
	v_mfma_f32_32x32x16_bf16 v[66:81], v[152:155], v[140:143], v[66:81]
	ds_read_b128 v[148:151], v216 offset:32768
	ds_read_b128 v[152:155], v216 offset:40960
	v_exp_f32_e32 v232, v88
	v_exp_f32_e32 v235, v89
	v_add_f32_e32 v202, v242, v202
	s_waitcnt lgkmcnt(3)
	v_mfma_f32_32x32x16_bf16 v[98:113], v[156:159], v[136:139], v[98:113]
	v_cvt_pk_bf16_f32 v82, v239, v240
	v_cvt_pk_bf16_f32 v83, v241, v242
	v_cvt_pk_bf16_f32 v84, v243, v244
	v_cvt_pk_bf16_f32 v85, v245, v246
	v_add_f32_e32 v202, v243, v202
	s_waitcnt lgkmcnt(2)
	v_mfma_f32_32x32x16_bf16 v[66:81], v[160:163], v[136:139], v[66:81]
	ds_read_b128 v[156:159], v215 offset:32768
	ds_read_b128 v[160:163], v215 offset:40960
	v_add_f32_e32 v202, v244, v202
	v_add_f32_e32 v202, v245, v202
	v_permlane32_swap_b32_e32 v82, v84
	v_permlane32_swap_b32_e32 v83, v85
	v_exp_f32_e32 v199, v90
	s_waitcnt lgkmcnt(3)
	v_mfma_f32_32x32x16_bf16 v[98:113], v[148:151], v[132:135], v[98:113]
	v_exp_f32_e32 v200, v91
	v_add_f32_e32 v202, v246, v202
	v_add_f32_e32 v202, v247, v202
	v_add_f32_e32 v202, v248, v202
	s_waitcnt lgkmcnt(2)
	v_mfma_f32_32x32x16_bf16 v[66:81], v[152:155], v[132:135], v[66:81]
	ds_read_b128 v[148:151], v214 offset:32768
	ds_read_b128 v[152:155], v214 offset:40960
	v_cvt_pk_bf16_f32 v86, v247, v248
	v_cvt_pk_bf16_f32 v87, v249, v250
	v_cvt_pk_bf16_f32 v88, v251, v252
	v_cvt_pk_bf16_f32 v89, v182, v183
	v_add_f32_e32 v202, v249, v202
	s_waitcnt lgkmcnt(3)
	v_mfma_f32_32x32x16_bf16 v[98:113], v[156:159], v[128:131], v[98:113]
	v_add_f32_e32 v202, v250, v202
	v_add_f32_e32 v202, v251, v202
	v_permlane32_swap_b32_e32 v86, v88
	v_permlane32_swap_b32_e32 v87, v89
	s_waitcnt vmcnt(0)
	ds_write_b128 v220, v[172:175] offset:49152
	ds_write_b128 v222, v[176:179] offset:49152
	s_waitcnt lgkmcnt(4)
; #define SBAR() __builtin_amdgcn_sched_barrier(0)
; #define SLOAD(i, k0) do { const char* vb_ = (const char*)Vh + (size_t)(k0) * (LDV * 2); const char* kb_ = (const char*)Kh + (size_t)(k0) * (LDKK * 2); \
;     sr_[i].vs0 = *(const bf16x8*)(vb_ + voff); sr_[i].vs1 = *(const bf16x8*)(vb_ + 32 * LDV * 2 + voff); \
;     sr_[i].ks0 = *(const bf16x8*)(kb_ + koff); sr_[i].ks1 = *(const bf16x8*)(kb_ + 32 * LDKK * 2 + koff); } while (0)
; #define SWAIT() asm volatile("s_waitcnt vmcnt(4)" ::: "memory")
; template <int D0> __device__ __forceinline__ void pv_one(f32x16& od, int vb, bf16x8 pa0, bf16x8 pa1, bf16x8 pa2, bf16x8 pa3) {
;   const s16x4 l0 = tr_read<v_rd_off(D0, 0, 0)>(vb), h0 = tr_read<v_rd_off(D0, 0, 1)>(vb), l1 = tr_read<v_rd_off(D0, 1, 0)>(vb), h1 = tr_read<v_rd_off(D0, 1, 1)>(vb);
;   const s16x4 l2 = tr_read<v_rd_off(D0, 2, 0)>(vb), h2 = tr_read<v_rd_off(D0, 2, 1)>(vb), l3 = tr_read<v_rd_off(D0, 3, 0)>(vb), h3 = tr_read<v_rd_off(D0, 3, 1)>(vb);
;   asm volatile("s_waitcnt lgkmcnt(0)" ::: "memory"); SBAR();
;   od = __builtin_amdgcn_mfma_f32_32x32x16_bf16(pa0, ATT_PK(l0, h0), od, 0, 0, 0);
;   od = __builtin_amdgcn_mfma_f32_32x32x16_bf16(pa1, ATT_PK(l1, h1), od, 0, 0, 0);
;   od = __builtin_amdgcn_mfma_f32_32x32x16_bf16(pa2, ATT_PK(l2, h2), od, 0, 0, 0);
;   od = __builtin_amdgcn_mfma_f32_32x32x16_bf16(pa3, ATT_PK(l3, h3), od, 0, 0, 0);
; }
; __device__ __forceinline__ void pv_d0(f32x16* o, int vb, bf16x8 pa0, bf16x8 pa1, bf16x8 pa2, bf16x8 pa3) {
;   pv_one<0>(o[0], vb, pa0, pa1, pa2, pa3); pv_one<1>(o[1], vb, pa0, pa1, pa2, pa3); pv_one<2>(o[2], vb, pa0, pa1, pa2, pa3); pv_one<3>(o[3], vb, pa0, pa1, pa2, pa3);
; template <bool FAST> __device__ __forceinline__ void attn_dense_body(const bf16_t* __restrict__ Qb, const bf16_t* __restrict__ Kh, const bf16_t* __restrict__ Vh, ...
;     ...
;     SBAR(); qkt(pA0, pA1, K_lds, qr, r32, hi);
;     fsm<FAST>(pB0, pB1, alB, l_reg, pa0, pa1, pa2, pa3); SBAR();
;     if (j + 3 < NT) SLOAD(SE, (j + 3) * KVBLK); SBAR();
;     pv_d0(o, vb0 + (int)SHM_V, pa0, pa1, pa2, pa3); psm<FAST>(pA0, pA1, m_reg, mnA, alA);
;     __syncthreads(); SWAIT(); SWRITE(1, SO);
;     if constexpr (!FAST) RESC(alA); __syncthreads();
;   }
	v_mfma_f32_32x32x16_bf16 v[66:81], v[160:163], v[128:131], v[66:81]
	ds_read_b128 v[156:159], v213 offset:32768
	ds_read_b128 v[160:163], v213 offset:40960
	v_exp_f32_e32 v201, v92
	v_exp_f32_e32 v227, v93
	v_add_f32_e32 v202, v252, v202
	s_waitcnt lgkmcnt(5)
	v_mfma_f32_32x32x16_bf16 v[98:113], v[148:151], v[124:127], v[98:113]
	v_exp_f32_e32 v198, v94
	v_exp_f32_e32 v225, v95
	v_add_f32_e32 v202, v182, v202
	s_waitcnt lgkmcnt(4)
	v_mfma_f32_32x32x16_bf16 v[66:81], v[152:155], v[124:127], v[66:81]
	ds_read_b128 v[148:151], v224 offset:32768
	ds_read_b128 v[152:155], v224 offset:40960
	v_exp_f32_e32 v226, v96
	v_exp_f32_e32 v228, v97
	v_add_f32_e32 v202, v183, v202
	s_waitcnt lgkmcnt(3)
	v_mfma_f32_32x32x16_bf16 v[98:113], v[156:159], v[120:123], v[98:113]
	v_cvt_pk_bf16_f32 v90, v229, v230
	v_cvt_pk_bf16_f32 v91, v231, v233
	v_cvt_pk_bf16_f32 v92, v234, v236
	v_cvt_pk_bf16_f32 v93, v232, v235
	s_waitcnt lgkmcnt(2)
	v_mfma_f32_32x32x16_bf16 v[66:81], v[160:163], v[120:123], v[66:81]
	v_cvt_pk_bf16_f32 v94, v199, v200
	v_cvt_pk_bf16_f32 v95, v201, v227
	v_permlane32_swap_b32_e32 v90, v92
	v_permlane32_swap_b32_e32 v91, v93
	ds_read_b64_tr_b16 v[240:241], v115 offset:0
	ds_read_b64_tr_b16 v[242:243], v115 offset:2048
	s_waitcnt lgkmcnt(3)
	v_mfma_f32_32x32x16_bf16 v[98:113], v[148:151], v[116:119], v[98:113]
	v_cvt_pk_bf16_f32 v96, v198, v225
	v_cvt_pk_bf16_f32 v97, v226, v228
	ds_read_b64_tr_b16 v[244:245], v115 offset:4096
	ds_read_b64_tr_b16 v[246:247], v115 offset:6144
	ds_read_b64_tr_b16 v[248:249], v115 offset:8192
	ds_read_b64_tr_b16 v[250:251], v115 offset:10240
	s_waitcnt lgkmcnt(6)
	v_mfma_f32_32x32x16_bf16 v[66:81], v[152:155], v[116:119], v[66:81]
	ds_read_b64_tr_b16 v[190:191], v115 offset:12288
	ds_read_b64_tr_b16 v[192:193], v115 offset:14336
	v_permlane32_swap_b32_e32 v94, v96
	v_permlane32_swap_b32_e32 v95, v97
	s_cmpk_gt_u32 s8, 0x7c
	s_cbranch_scc1 .Lattn_h2c_last
	s_waitcnt lgkmcnt(6)
	v_mfma_f32_32x32x16_bf16 v[2:17], v[82:85], v[240:243], v[2:17]
	ds_read_b64_tr_b16 v[240:241], v115 offset:512
	ds_read_b64_tr_b16 v[242:243], v115 offset:2560
	v_add_f32_e32 v202, v229, v202
	v_exp_f32_e32 v229, v98
	v_lshl_add_u64 v[188:189], v[196:197], 0, s[48:49]
	v_lshl_add_u64 v[186:187], v[194:195], 0, s[48:49]
	s_waitcnt lgkmcnt(6)
	v_mfma_f32_32x32x16_bf16 v[2:17], v[86:89], v[244:247], v[2:17]
	ds_read_b64_tr_b16 v[244:245], v115 offset:4608
	ds_read_b64_tr_b16 v[246:247], v115 offset:6656
	v_add_f32_e32 v202, v230, v202
	v_exp_f32_e32 v230, v99
	v_add_co_u32_e32 v148, vcc, 0x4d684000, v188
	s_waitcnt lgkmcnt(6)
	v_mfma_f32_32x32x16_bf16 v[2:17], v[90:93], v[248:251], v[2:17]
	ds_read_b64_tr_b16 v[248:249], v115 offset:8704
	ds_read_b64_tr_b16 v[250:251], v115 offset:10752
	v_add_f32_e32 v202, v231, v202
	v_exp_f32_e32 v231, v100
	v_addc_co_u32_e32 v149, vcc, 0, v189, vcc
	v_add_co_u32_e32 v152, vcc, 0x4d714000, v188
	s_waitcnt lgkmcnt(6)
	v_mfma_f32_32x32x16_bf16 v[2:17], v[94:97], v[190:193], v[2:17]
	ds_read_b64_tr_b16 v[190:191], v115 offset:12800
	ds_read_b64_tr_b16 v[192:193], v115 offset:14848
	v_add_f32_e32 v202, v233, v202
	v_exp_f32_e32 v233, v101
	global_load_dwordx4 v[148:151], v[148:149], off offset:1024
	v_addc_co_u32_e32 v153, vcc, 0, v189, vcc
	v_add_co_u32_e32 v156, vcc, 0x5f240000, v186
	s_waitcnt lgkmcnt(6)
	v_mfma_f32_32x32x16_bf16 v[18:33], v[82:85], v[240:243], v[18:33]
	ds_read_b64_tr_b16 v[240:241], v115 offset:1024
	ds_read_b64_tr_b16 v[242:243], v115 offset:3072
	v_add_f32_e32 v202, v234, v202
	v_exp_f32_e32 v234, v102
	global_load_dwordx4 v[152:155], v[152:153], off offset:1024
	v_addc_co_u32_e32 v157, vcc, 0, v187, vcc
	v_add_co_u32_e32 v160, vcc, 0x5f248000, v186
	s_waitcnt lgkmcnt(6)
	v_mfma_f32_32x32x16_bf16 v[18:33], v[86:89], v[244:247], v[18:33]
	ds_read_b64_tr_b16 v[244:245], v115 offset:5120
	ds_read_b64_tr_b16 v[246:247], v115 offset:7168
	v_add_f32_e32 v202, v236, v202
	v_exp_f32_e32 v236, v103
	global_load_dwordx4 v[156:159], v[156:157], off
	v_addc_co_u32_e32 v161, vcc, 0, v187, vcc
	s_waitcnt lgkmcnt(6)
	v_mfma_f32_32x32x16_bf16 v[18:33], v[90:93], v[248:251], v[18:33]
	ds_read_b64_tr_b16 v[248:249], v115 offset:9216
	ds_read_b64_tr_b16 v[250:251], v115 offset:11264
	v_add_f32_e32 v202, v232, v202
	v_exp_f32_e32 v232, v104
	v_add_f32_e32 v202, v235, v202
	v_exp_f32_e32 v235, v105
	global_load_dwordx4 v[160:163], v[160:161], off
	s_waitcnt lgkmcnt(6)
	v_mfma_f32_32x32x16_bf16 v[18:33], v[94:97], v[190:193], v[18:33]
	ds_read_b64_tr_b16 v[190:191], v115 offset:13312
	ds_read_b64_tr_b16 v[192:193], v115 offset:15360
	v_add_f32_e32 v202, v199, v202
	v_exp_f32_e32 v199, v106
	v_add_f32_e32 v202, v200, v202
	v_exp_f32_e32 v200, v107
	s_waitcnt lgkmcnt(6)
	v_mfma_f32_32x32x16_bf16 v[34:49], v[82:85], v[240:243], v[34:49]
	ds_read_b64_tr_b16 v[240:241], v115 offset:1536
	ds_read_b64_tr_b16 v[242:243], v115 offset:3584
	v_add_f32_e32 v202, v201, v202
	v_exp_f32_e32 v201, v108
	v_add_f32_e32 v202, v227, v202
	v_exp_f32_e32 v227, v109
	s_waitcnt lgkmcnt(6)
	v_mfma_f32_32x32x16_bf16 v[34:49], v[86:89], v[244:247], v[34:49]
	ds_read_b64_tr_b16 v[244:245], v115 offset:5632
	ds_read_b64_tr_b16 v[246:247], v115 offset:7680
	v_add_f32_e32 v202, v198, v202
	v_exp_f32_e32 v198, v110
	v_add_f32_e32 v202, v225, v202
	v_exp_f32_e32 v225, v111
	s_waitcnt lgkmcnt(6)
	v_mfma_f32_32x32x16_bf16 v[34:49], v[90:93], v[248:251], v[34:49]
	ds_read_b64_tr_b16 v[248:249], v115 offset:9728
	ds_read_b64_tr_b16 v[250:251], v115 offset:11776
	v_add_f32_e32 v202, v226, v202
	v_exp_f32_e32 v226, v112
	v_add_f32_e32 v202, v228, v202
	v_exp_f32_e32 v228, v113
	s_waitcnt lgkmcnt(6)
	v_mfma_f32_32x32x16_bf16 v[34:49], v[94:97], v[190:193], v[34:49]
	ds_read_b64_tr_b16 v[190:191], v115 offset:13824
	ds_read_b64_tr_b16 v[192:193], v115 offset:15872
	v_mov_b32_e32 v238, v202
	s_waitcnt lgkmcnt(0)
	v_mfma_f32_32x32x16_bf16 v[50:65], v[82:85], v[240:243], v[50:65]
	s_barrier
	ds_write_b128 v217, v[164:167] offset:16384
	ds_write_b128 v218, v[168:171] offset:16384
	ds_read_b128 v[172:175], v221 offset:49152
	ds_read_b128 v[176:179], v221 offset:57344
	v_permlane32_swap_b32_e32 v202, v238
	v_mfma_f32_32x32x16_bf16 v[50:65], v[86:89], v[244:247], v[50:65]
	v_add_f32_e32 v238, v202, v238
	v_add_f32_e32 v1, v1, v238
	ds_read_b128 v[164:167], v223 offset:49152
	ds_read_b128 v[168:171], v223 offset:57344
	v_mfma_f32_32x32x16_bf16 v[50:65], v[90:93], v[248:251], v[50:65]
	v_mfma_f32_32x32x16_bf16 v[50:65], v[94:97], v[190:193], v[50:65]
	v_lshl_add_u64 v[194:195], v[194:195], 0, s[30:31]
	v_lshl_add_u64 v[196:197], v[196:197], 0, s[80:81]
	s_add_i32 s8, s8, 2
	s_branch .Lattn_h1
